# Loop-edge edits combined: scan ring offset carried from the loop tail, record-builder pointer kept in registers, counted wait at the scan mid barrier (all on the MFMA/VALU-interleaved scan)
# baseline (speedup 1.0000x reference)
.LBB0_433:
	v_add_u32_e32 v136, s1, v151
	ds_read_b128 v[228:231], v136 offset:17792
	ds_read_b128 v[232:235], v136 offset:17824
	ds_read_b128 v[236:239], v136 offset:17856
	ds_read_b128 v[240:243], v136 offset:17888
	ds_read_b128 v[128:131], v136 offset:17920
	ds_read_b128 v[132:135], v136 offset:17952
	ds_read_b128 v[220:223], v136 offset:17984
	ds_read_b128 v[224:227], v136 offset:18016
	v_cvt_pk_bf16_f32 v112, v16, v17
	v_cvt_pk_bf16_f32 v113, v18, v19
	v_cvt_pk_bf16_f32 v114, v20, v21
	v_cvt_pk_bf16_f32 v115, v22, v23
	v_cvt_pk_bf16_f32 v116, v24, v25
	v_cvt_pk_bf16_f32 v117, v26, v27
	v_cvt_pk_bf16_f32 v118, v28, v29
	v_cvt_pk_bf16_f32 v119, v30, v31
	s_nop 1
	v_mfma_f32_32x32x16_bf16 v[32:47], v[48:51], v[112:115], 0
	v_mfma_f32_32x32x16_bf16 v[32:47], v[52:55], v[116:119], v[32:47]
	v_cvt_pk_bf16_f32 v120, v0, v1
	v_cvt_pk_bf16_f32 v121, v2, v3
	v_cvt_pk_bf16_f32 v122, v4, v5
	v_cvt_pk_bf16_f32 v123, v6, v7
	v_cvt_pk_bf16_f32 v124, v8, v9
	v_cvt_pk_bf16_f32 v125, v10, v11
	v_cvt_pk_bf16_f32 v126, v12, v13
	v_cvt_pk_bf16_f32 v127, v14, v15
	s_waitcnt lgkmcnt(0)
	v_pk_mul_f32 v[16:17], v[16:17], v[228:229]
	v_pk_mul_f32 v[18:19], v[18:19], v[230:231]
	v_pk_mul_f32 v[20:21], v[20:21], v[232:233]
	v_pk_mul_f32 v[22:23], v[22:23], v[234:235]
	v_pk_mul_f32 v[24:25], v[24:25], v[236:237]
	v_pk_mul_f32 v[26:27], v[26:27], v[238:239]
	v_pk_mul_f32 v[28:29], v[28:29], v[240:241]
	v_pk_mul_f32 v[30:31], v[30:31], v[242:243]
	v_mul_f32_e64 v0, v0, v128
	v_mul_f32_e64 v1, v1, v129
	v_mul_f32_e64 v2, v2, v130
	v_mul_f32_e64 v3, v3, v131
	v_mul_f32_e64 v4, v4, v132
	v_mul_f32_e64 v5, v5, v133
	v_pk_mul_f32 v[6:7], v[6:7], v[134:135]
	s_or_b32 s1, s0, 1
	v_mfma_f32_32x32x16_bf16 v[16:31], v[72:75], v[112:115], v[16:31]
	s_and_b32 s2, s1, 0xff
	v_mul_f32_e64 v8, v8, v220
	v_mul_f32_e64 v9, v9, v221
	v_mul_f32_e64 v10, v10, v222
	v_mul_f32_e64 v11, v11, v223
	v_pk_mul_f32 v[12:13], v[12:13], v[224:225]
	v_pk_mul_f32 v[14:15], v[14:15], v[226:227]
	s_mul_i32 s2, s2, 37
	s_lshr_b32 s2, s2, 8
	s_sub_i32 s3, s1, s2
	s_bfe_u32 s3, s3, 0x70001
	s_add_i32 s3, s3, s2
	s_lshr_b32 s2, s3, 2
	s_mul_i32 s2, s2, 7
	s_sub_i32 s1, s1, s2
	s_and_b32 s1, s1, 0xff
	v_mfma_f32_32x32x16_bf16 v[0:15], v[88:91], v[112:115], v[0:15]
	s_mulk_i32 s1, 0x4800
	s_add_i32 s1, s1, 0
	v_add_u32_e32 v192, s1, v144
	v_add_u32_e32 v180, v192, v156
	s_cmpk_gt_u32 s0, 0x7d
	s_cselect_b64 s[2:3], -1, 0
	v_mfma_f32_32x32x16_bf16 v[16:31], v[76:79], v[116:119], v[16:31]
	s_and_b64 vcc, exec, s[2:3]
	v_mfma_f32_32x32x16_bf16 v[32:47], v[56:59], v[120:123], v[32:47]
	v_mfma_f32_32x32x16_bf16 v[0:15], v[92:95], v[116:119], v[0:15]
	v_mfma_f32_32x32x16_bf16 v[16:31], v[80:83], v[120:123], v[16:31]
	v_mfma_f32_32x32x16_bf16 v[32:47], v[60:63], v[124:127], v[32:47]
	v_mfma_f32_32x32x16_bf16 v[0:15], v[96:99], v[120:123], v[0:15]
	v_mfma_f32_32x32x16_bf16 v[16:31], v[84:87], v[124:127], v[16:31]
	v_mfma_f32_32x32x16_bf16 v[32:47], v[68:71], v[64:67], v[32:47]
	v_mfma_f32_32x32x16_bf16 v[0:15], v[100:103], v[124:127], v[0:15]
	s_nop 10
	v_add_u32_e32 v45, s1, v153
	v_add_u32_e32 v46, v45, v152
	v_add_u32_e32 v160, v45, v155
	v_add_u32_e32 v44, v192, v150
	ds_read2_b64 v[40:43], v46 offset1:2
	ds_read2_b64 v[116:119], v46 offset0:4 offset1:6
	ds_read2_b64 v[120:123], v46 offset0:8 offset1:10
	ds_read2_b64 v[124:127], v46 offset0:12 offset1:14
	v_add_u32_e32 v46, v192, v154
	v_add_u32_e32 v132, 0x800, v160
	v_mfma_f32_32x32x16_bf16 v[16:31], v[104:107], v[64:67], v[16:31]
	v_add_u32_e32 v172, 0x1800, v160
	ds_read_b128 v[112:115], v44 offset:14720
	ds_read_b128 v[128:131], v46 offset:2176
	ds_read2_b64 v[44:47], v132 offset0:112 offset1:114
	ds_read2_b64 v[140:143], v132 offset0:116 offset1:118
	ds_write2st64_b32 v158, v32, v33 offset1:1
	ds_write2st64_b32 v158, v34, v35 offset0:2 offset1:3
	ds_write2st64_b32 v158, v36, v37 offset0:8 offset1:9
	ds_write2st64_b32 v158, v38, v39 offset0:10 offset1:11
	ds_read2_b64 v[136:139], v132 offset0:120 offset1:122
	ds_read2_b64 v[132:135], v132 offset0:124 offset1:126
	ds_read2_b64 v[160:163], v172 offset0:144 offset1:146
	ds_read2_b64 v[164:167], v172 offset0:148 offset1:150
	ds_read2_b64 v[168:171], v172 offset0:152 offset1:154
	ds_read2_b64 v[172:175], v172 offset0:156 offset1:158
	ds_read_b128 v[176:179], v180 offset:11648
	ds_read_b128 v[180:183], v180 offset:13184
	ds_read_b128 v[220:223], v192 offset:17888
	ds_read_b128 v[224:227], v192 offset:17856
	ds_read_b128 v[228:231], v192 offset:17824
	ds_read_b128 v[232:235], v192 offset:17792
	ds_read_b128 v[236:239], v192 offset:18016
	ds_read_b128 v[240:243], v192 offset:17984
	ds_read_b128 v[244:247], v192 offset:17952
	s_waitcnt lgkmcnt(15)
	s_barrier
	ds_read_b128 v[36:39], v192 offset:17920
	v_cvt_pk_bf16_f32 v32, v16, v17
	v_mfma_f32_32x32x16_bf16 v[0:15], v[108:111], v[64:67], v[0:15]
	v_cvt_pk_bf16_f32 v33, v18, v19
	v_cvt_pk_bf16_f32 v34, v20, v21
	v_cvt_pk_bf16_f32 v35, v22, v23
	v_cvt_pk_bf16_f32 v184, v24, v25
	v_cvt_pk_bf16_f32 v185, v26, v27
	v_cvt_pk_bf16_f32 v186, v28, v29
	v_cvt_pk_bf16_f32 v187, v30, v31
	v_cvt_pk_bf16_f32 v188, v0, v1
	v_cvt_pk_bf16_f32 v189, v2, v3
	v_cvt_pk_bf16_f32 v190, v4, v5
	v_cvt_pk_bf16_f32 v191, v6, v7
	v_cvt_pk_bf16_f32 v216, v8, v9
	v_cvt_pk_bf16_f32 v217, v10, v11
	v_cvt_pk_bf16_f32 v218, v12, v13
	v_cvt_pk_bf16_f32 v219, v14, v15
	s_waitcnt lgkmcnt(1)
	v_pk_mul_f32 v[28:29], v[28:29], v[220:221]
	v_pk_mul_f32 v[30:31], v[30:31], v[222:223]
	v_pk_mul_f32 v[24:25], v[24:25], v[224:225]
	v_pk_mul_f32 v[26:27], v[26:27], v[226:227]
	v_pk_mul_f32 v[20:21], v[20:21], v[228:229]
	v_pk_mul_f32 v[22:23], v[22:23], v[230:231]
	v_pk_mul_f32 v[18:19], v[18:19], v[234:235]
	v_pk_mul_f32 v[16:17], v[16:17], v[232:233]
	v_pk_mul_f32 v[12:13], v[12:13], v[236:237]
	v_pk_mul_f32 v[14:15], v[14:15], v[238:239]
	v_mfma_f32_32x32x16_bf16 v[16:31], v[44:47], v[32:35], v[16:31]
	v_mul_f32_e64 v8, v8, v240
	v_mul_f32_e64 v9, v9, v241
	v_mul_f32_e64 v10, v10, v242
	v_mul_f32_e64 v11, v11, v243
	v_pk_mul_f32 v[4:5], v[4:5], v[244:245]
	v_pk_mul_f32 v[6:7], v[6:7], v[246:247]
	v_mfma_f32_32x32x16_bf16 v[16:31], v[140:143], v[184:187], v[16:31]
	s_waitcnt lgkmcnt(0)
	v_mul_f32_e64 v2, v2, v38
	v_mul_f32_e64 v3, v3, v39
	v_mul_f32_e64 v0, v0, v36
	v_mul_f32_e64 v1, v1, v37
	s_nop 1
	v_mfma_f32_32x32x16_bf16 v[0:15], v[160:163], v[32:35], v[0:15]
	v_mfma_f32_32x32x16_bf16 v[32:47], v[40:43], v[32:35], 0
	v_mfma_f32_32x32x16_bf16 v[32:47], v[116:119], v[184:187], v[32:47]
	v_mfma_f32_32x32x16_bf16 v[0:15], v[164:167], v[184:187], v[0:15]
	v_mfma_f32_32x32x16_bf16 v[32:47], v[120:123], v[188:191], v[32:47]
	v_mfma_f32_32x32x16_bf16 v[16:31], v[136:139], v[188:191], v[16:31]
	v_mfma_f32_32x32x16_bf16 v[0:15], v[168:171], v[188:191], v[0:15]
	v_mfma_f32_32x32x16_bf16 v[32:47], v[124:127], v[216:219], v[32:47]
	v_mfma_f32_32x32x16_bf16 v[16:31], v[132:135], v[216:219], v[16:31]
	v_mfma_f32_32x32x16_bf16 v[0:15], v[172:175], v[216:219], v[0:15]
	v_mfma_f32_32x32x16_bf16 v[32:47], v[128:131], v[112:115], v[32:47]
	v_mfma_f32_32x32x16_bf16 v[16:31], v[176:179], v[112:115], v[16:31]
	v_mfma_f32_32x32x16_bf16 v[0:15], v[180:183], v[112:115], v[0:15]
	s_cbranch_vccnz .LBB0_432
	s_add_i32 s1, s0, 2
	s_and_b32 s4, s1, 0xff
	s_mul_i32 s4, s4, 37
	s_lshr_b32 s5, s4, 8
	s_sub_i32 s5, s1, s5
	s_bfe_u32 s5, s5, 0x70001
	s_bfe_u32 s4, s4, 0x80008
	s_add_i32 s5, s5, s4
	s_bfe_u32 s4, s5, 0x60002
	s_mul_i32 s4, s4, 7
	s_sub_i32 s1, s1, s4
	s_and_b32 s1, s1, 0xff
	s_mulk_i32 s1, 0x4800
	s_add_i32 s1, s1, 0
	v_add_u32_e32 v40, s1, v144
	v_add_u32_e32 v42, s1, v153
	v_add_u32_e32 v41, v40, v150
	v_add_u32_e32 v43, v42, v152
	ds_read2_b64 v[48:51], v43 offset1:2
	ds_read2_b64 v[52:55], v43 offset0:4 offset1:6
	ds_read2_b64 v[56:59], v43 offset0:8 offset1:10
	ds_read2_b64 v[60:63], v43 offset0:12 offset1:14
	v_add_u32_e32 v43, v40, v154
	ds_read_b128 v[64:67], v41 offset:14720
	ds_read_b128 v[68:71], v43 offset:2176
	v_add_u32_e32 v41, v42, v155
	v_add_u32_e32 v42, 0x800, v41
	v_add_u32_e32 v41, 0x1800, v41
	ds_read2_b64 v[72:75], v42 offset0:112 offset1:114
	ds_read2_b64 v[76:79], v42 offset0:116 offset1:118
	ds_read2_b64 v[80:83], v42 offset0:120 offset1:122
	ds_read2_b64 v[84:87], v42 offset0:124 offset1:126
	v_add_u32_e32 v40, v40, v156
	ds_read2_b64 v[88:91], v41 offset0:144 offset1:146
	ds_read2_b64 v[92:95], v41 offset0:148 offset1:150
	ds_read2_b64 v[96:99], v41 offset0:152 offset1:154
	ds_read2_b64 v[100:103], v41 offset0:156 offset1:158
	ds_read_b128 v[104:107], v40 offset:11648
	ds_read_b128 v[108:111], v40 offset:13184
	s_branch .LBB0_432
